# attention: per-lane column offset folded into the V^T tile pointers once per unit (two 64-bit adds fewer per step)
# baseline (speedup 1.0000x reference)
.LBB0_276:
	s_or_b32 s46, s9, s79
	s_and_b32 s98, s46, 7
	s_add_i32 s0, s98, 1
	v_cvt_f32_ubyte0_e32 v0, s0
	s_mov_b32 s0, 0x42fc0000
	v_cmp_lt_f32_e32 vcc, s0, v0
	s_and_b64 s[0:1], vcc, exec
	s_cselect_b32 s0, 0xffffffc0, 0
	v_cndmask_b32_e32 v1, 0, v157, vcc
	v_sub_f32_e32 v0, v1, v0
	v_exp_f32_e32 v0, v0
	v_mov_b32_e32 v1, v152
	s_bitcmp0_b32 s9, 0
	v_ldexp_f32 v0, v0, s0
	v_mul_f32_e32 v138, 0x3fb8aa3b, v0
	v_bfe_u32 v0, v1, 3, 1
	v_lshlrev_b32_e32 v169, 3, v1
	v_mul_u32_u24_e32 v9, 0x2400, v0
	v_and_b32_e32 v0, 56, v169
	v_ashrrev_i32_e32 v2, 4, v1
	v_mad_u64_u32 v[4:5], s[34:35], v2, s80, v[0:1]
	v_ashrrev_i32_e32 v10, 3, v1
	v_lshl_add_u32 v175, v4, 1, v9
	v_mul_lo_u32 v4, v10, s80
	v_add_u32_e32 v11, 0x200, v1
	v_add_lshl_u32 v176, v4, v0, 1
	v_ashrrev_i32_e32 v4, 4, v11
	v_mad_u64_u32 v[6:7], s[34:35], v4, s80, v[0:1]
	v_lshl_add_u32 v177, v6, 1, v9
	v_ashrrev_i32_e32 v6, 3, v11
	v_mul_lo_u32 v7, v6, s80
	v_add_lshl_u32 v178, v7, v0, 1
	v_add_u32_e32 v0, 0, v175
	s_waitcnt vmcnt(3)
	ds_write_b128 v0, v[118:121]
	v_add_u32_e32 v0, 0, v176
	s_waitcnt vmcnt(2)
	ds_write_b128 v0, v[114:117] offset:18432
	v_add_u32_e32 v0, 0, v177
	s_waitcnt vmcnt(1)
	ds_write_b128 v0, v[122:125]
	v_add_u32_e32 v0, 0, v178
	v_lshlrev_b32_e32 v7, 1, v1
	v_lshrrev_b32_e32 v9, 1, v1
	s_waitcnt vmcnt(0)
	ds_write_b128 v0, v[126:129] offset:18432
	v_and_b32_e32 v0, 19, v1
	v_and_b32_e32 v7, 8, v7
	v_and_b32_e32 v9, 4, v9
	v_or3_b32 v0, v0, v7, v9
	v_mul_u32_u24_e32 v179, 0x90, v0
	v_and_b32_e32 v0, 7, v1
	v_lshlrev_b32_e32 v96, 4, v0
	v_add_u32_e32 v0, s8, v10
	v_and_b32_e32 v171, 31, v1
	v_readfirstlane_b32 s65, v1
	v_and_b32_e32 v168, 63, v1
	v_bfe_u32 v170, v1, 5, 1
	v_and_b32_e32 v8, 15, v1
	v_ashrrev_i32_e32 v1, 31, v0
	v_lshlrev_b64 v[0:1], 15, v[0:1]
	s_cselect_b64 s[0:1], -1, 0
	v_lshl_add_u64 v[144:145], s[42:43], 0, v[0:1]
	v_lshl_add_u64 v[144:145], v[144:145], 0, v[96:97]
	v_add_u32_e32 v0, s8, v6
	s_and_b64 s[34:35], s[0:1], exec
	v_ashrrev_i32_e32 v1, 31, v0
	s_cselect_b32 s38, s77, s78
	s_and_b32 s48, s65, 0x3fffffc0
	v_ashrrev_i32_e32 v3, 31, v2
	v_lshlrev_b64 v[0:1], 15, v[0:1]
	s_lshl_b32 s49, s38, 7
	s_lshl_b32 s34, s48, 2
	v_lshl_add_u64 v[146:147], s[42:43], 0, v[0:1]
	v_lshl_add_u64 v[146:147], v[146:147], 0, v[96:97]
	v_lshlrev_b64 v[0:1], 11, v[2:3]
	v_lshlrev_b32_e32 v2, 4, v8
	v_ashrrev_i32_e32 v5, 31, v4
	s_add_i32 s66, s34, 0
	s_or_b32 s34, s49, 0x7f
	v_or_b32_e32 v0, v0, v2
	s_bfe_u32 s64, s65, 0x20006
	v_cvt_f32_u32_e32 v181, s34
	v_lshl_add_u64 v[148:149], s[86:87], 0, v[0:1]
	v_lshlrev_b64 v[0:1], 11, v[4:5]
	s_lshl_b32 s39, s64, 5
	v_or_b32_e32 v0, v0, v2
	v_mov_b32_e32 v14, v97
	v_mov_b32_e32 v15, v97
	s_or_b32 s99, s39, s49
	s_lshl_b32 s69, s38, 1
	s_add_i32 s66, s66, 0x1b000
	v_lshl_add_u64 v[150:151], s[86:87], 0, v[0:1]
	v_mov_b32_e32 v0, v97
	v_mov_b32_e32 v1, v97
	v_mov_b32_e32 v2, v97
	v_mov_b32_e32 v3, v97
	v_mov_b32_e32 v4, v97
	v_mov_b32_e32 v5, v97
	v_mov_b32_e32 v6, v97
	v_mov_b32_e32 v7, v97
	v_mov_b32_e32 v8, v97
	v_mov_b32_e32 v9, v97
	v_mov_b32_e32 v10, v97
	v_mov_b32_e32 v11, v97
	v_mov_b32_e32 v12, v97
	v_mov_b32_e32 v13, v97
	v_mov_b64_e32 v[30:31], v[14:15]
	v_mov_b64_e32 v[46:47], v[14:15]
	v_mov_b64_e32 v[62:63], v[14:15]
	s_mov_b32 s68, 1
	s_ashr_i32 s67, s65, 8
	s_add_i32 s69, s69, 2
	v_lshlrev_b32_e32 v172, 4, v170
	v_mul_u32_u24_e32 v180, 0x90, v171
	s_or_b32 s70, s99, 31
	v_lshlrev_b32_e32 v182, 3, v170
	v_or_b32_e32 v183, s99, v171
	v_cmp_gt_u32_e64 s[38:39], 32, v168
	v_lshl_add_u32 v173, v171, 2, s66
	v_mov_b32_e32 v140, v138
	v_mov_b32_e32 v141, v138
	v_mov_b32_e32 v142, v138
	v_mov_b32_e32 v143, v138
	s_add_i32 s48, s49, 0x80
	v_mov_b32_e32 v174, 0
	s_mov_b32 s49, 0
	v_mov_b64_e32 v[28:29], v[12:13]
	v_mov_b64_e32 v[26:27], v[10:11]
	v_mov_b64_e32 v[24:25], v[8:9]
	v_mov_b64_e32 v[22:23], v[6:7]
	v_mov_b64_e32 v[20:21], v[4:5]
	v_mov_b64_e32 v[18:19], v[2:3]
	v_mov_b64_e32 v[16:17], v[0:1]
	v_mov_b64_e32 v[44:45], v[12:13]
	v_mov_b64_e32 v[42:43], v[10:11]
	v_mov_b64_e32 v[40:41], v[8:9]
	v_mov_b64_e32 v[38:39], v[6:7]
	v_mov_b64_e32 v[36:37], v[4:5]
	v_mov_b64_e32 v[34:35], v[2:3]
	v_mov_b64_e32 v[32:33], v[0:1]
	v_mov_b64_e32 v[60:61], v[12:13]
	v_mov_b64_e32 v[58:59], v[10:11]
	v_mov_b64_e32 v[56:57], v[8:9]
	v_mov_b64_e32 v[54:55], v[6:7]
	v_mov_b64_e32 v[52:53], v[4:5]
	v_mov_b64_e32 v[50:51], v[2:3]
	v_mov_b64_e32 v[48:49], v[0:1]
	s_mov_b32 s50, 0
	v_mov_b32_e32 v184, 0
	s_waitcnt lgkmcnt(0)
	s_barrier
	s_branch .LBB0_278

.LBB0_278:
	s_cmp_lt_u32 s68, s69
	s_cselect_b64 s[34:35], -1, 0
	s_cmp_ge_u32 s68, s69
	s_cbranch_scc1 .LBB0_280
	global_load_dwordx4 v[118:121], v[148:149], off
	global_load_dwordx4 v[114:117], v[144:145], off
	global_load_dwordx4 v[122:125], v[150:151], off
	global_load_dwordx4 v[126:129], v[146:147], off
